# v23 + redundant vmcnt(0) drain removed at the up-GEMM epilogue start (prefetched row-sum data is already complete)
# baseline (speedup 1.0000x reference)
; #define PG8_STAGE(bufoff, gbase, voff) do { _Pragma("unroll") for (int _i = 0; _i < 2; ++_i) \
;         __builtin_amdgcn_global_load_lds((const unsigned*)((const char*)(gbase) + (voff)[_i]), (LAS unsigned*)(lds + (bufoff) + ldsw + _i * 8192), 16, 0, 0); } while (0)
; #define PG8_LDA(dst, b, h) do { _Pragma("unroll") for (int m = 0; m < 4; ++m) _Pragma("unroll") for (int k = 0; k < 2; ++k) dst[m][k] = *(const LAS bf16x8*)(lds + PG8_SA(b, h) + aoff + m * 2048 + k * 1024); } while (0)
; #define PG8_LDB(dst, b, h) do { _Pragma("unroll") for (int n = 0; n < 2; ++n) _Pragma("unroll") for (int k = 0; k < 2; ++k) dst[n][k] = *(const LAS bf16x8*)(lds + PG8_SB(b, h) + boff + n * 2048 + k * 1024); } while (0)
; #define PG8_MMA(ai, bj, At, Bt) do { __builtin_amdgcn_s_setprio(1); _Pragma("unroll") for (int m = 0; m < 4; ++m) _Pragma("unroll") for (int n = 0; n < 2; ++n) _Pragma("unroll") for (int k = 0; k < 2; ++k) \
;         acc[ai][bj][m][n] = __builtin_amdgcn_mfma_f32_16x16x32_bf16(Bt[n][k], At[m][k], acc[ai][bj][m][n], 0, 0, 0); __builtin_amdgcn_s_setprio(0); } while (0)
; #define PG8_WAIT_V(n) asm volatile("s_waitcnt vmcnt(" #n ")" ::: "memory")
; template <class Epi, class Sched>
; __device__ __forceinline__ void gemm_phase(const int wv, LAS unsigned char* lds, const Gemm g, const Sched& S, const Epi& E) {
;     ...
;         for (int t = 0; t < nt; t += 2) {
;             const bool last = (t == nt - 2);
;             const char* a1 = cA + (size_t)(t + 1) * kstepA;
;             const char* a2 = last ? nA : cA + (size_t)(t + 2) * kstepA; const char* b2 = last ? nB : cB + (size_t)(t + 2) * kstep;
;             const char* a3 = a2 + kstepA; const char* b3 = b2 + kstep;
;             if (last && has_next) S.a_ready(nxt);
;             PG8_LDB(B0, 0, 0); PG8_SCHED; PG8_LDA(At, 0, 0); PG8_STAGE(PG8_SA(1, 1), a1 + hstepA, voffA);
;             PG8_WAIT_L(8); PG8_BAR; PG8_WAIT_L(0); PG8_MMA(0, 0, At, B0); PG8_BAR; PG8_SCHED;
;             PG8_LDB(B1, 0, 1); PG8_STAGE(PG8_SB(0, 0), b2, voffB);
;             PG8_BAR; PG8_WAIT_L(0); PG8_MMA(0, 1, At, B1); PG8_BAR;
;             PG8_LDA(At, 0, 1); PG8_STAGE(PG8_SA(0, 0), a2, voffA);
;             PG8_BAR; PG8_WAIT_L(0); PG8_MMA(1, 0, At, B0); PG8_BAR; PG8_SCHED;
;             PG8_STAGE(PG8_SB(0, 1), b2 + hstepB, voffB);
;             PG8_WAIT_V(6); PG8_BAR; PG8_MMA(1, 1, At, B1); PG8_BAR;
.LBB0_725:
	ds_read_b128 v[128:131], v176
	ds_read_b128 v[132:135], v176 offset:1024
	ds_read_b128 v[136:139], v176 offset:2048
	ds_read_b128 v[140:143], v176 offset:3072
	s_add_u32 s18, s16, 0xfffc0080
	s_addc_u32 s19, s17, -1
	s_cmp_eq_u32 s46, 12
	s_cselect_b32 s21, s9, s19
	s_cselect_b32 s20, s42, s18
	s_cselect_b32 s19, s7, s45
	s_cselect_b32 s18, s43, s44
	v_lshl_add_u64 v[170:171], s[16:17], 0, v[160:161]
	s_add_i32 m0, s28, 0xc000
	ds_read_b128 v[144:147], v177
	ds_read_b128 v[182:185], v177 offset:1024
	ds_read_b128 v[186:189], v177 offset:2048
	ds_read_b128 v[190:193], v177 offset:3072
	ds_read_b128 v[194:197], v177 offset:4096
	ds_read_b128 v[198:201], v177 offset:5120
	ds_read_b128 v[202:205], v177 offset:6144
	ds_read_b128 v[206:209], v177 offset:7168
	global_load_lds_dwordx4 v[170:171], off
	s_add_i32 m0, s28, 0xe000
	v_lshl_add_u64 v[170:171], s[16:17], 0, v[162:163]
	global_load_lds_dwordx4 v[170:171], off
	s_waitcnt lgkmcnt(8)
	s_barrier
	s_waitcnt lgkmcnt(0)
	v_mfma_f32_16x16x32_bf16 v[124:127], v[128:131], v[144:147], v[124:127]
	v_mfma_f32_16x16x32_bf16 v[120:123], v[136:139], v[144:147], v[120:123]
	v_mfma_f32_16x16x32_bf16 v[108:111], v[128:131], v[186:189], v[108:111]
	v_mfma_f32_16x16x32_bf16 v[104:107], v[136:139], v[186:189], v[104:107]
	v_mfma_f32_16x16x32_bf16 v[92:95], v[128:131], v[194:197], v[92:95]
	v_mfma_f32_16x16x32_bf16 v[88:91], v[136:139], v[194:197], v[88:91]
	v_mfma_f32_16x16x32_bf16 v[76:79], v[128:131], v[202:205], v[76:79]
	v_mfma_f32_16x16x32_bf16 v[72:75], v[136:139], v[202:205], v[72:75]
	v_mfma_f32_16x16x32_bf16 v[124:127], v[132:135], v[182:185], v[124:127]
	v_mfma_f32_16x16x32_bf16 v[120:123], v[140:143], v[182:185], v[120:123]
	v_mfma_f32_16x16x32_bf16 v[108:111], v[132:135], v[190:193], v[108:111]
	v_mfma_f32_16x16x32_bf16 v[104:107], v[140:143], v[190:193], v[104:107]
	v_mfma_f32_16x16x32_bf16 v[92:95], v[132:135], v[198:201], v[92:95]
	v_mfma_f32_16x16x32_bf16 v[88:91], v[140:143], v[198:201], v[88:91]
	v_mfma_f32_16x16x32_bf16 v[76:79], v[132:135], v[206:209], v[76:79]
	v_mfma_f32_16x16x32_bf16 v[72:75], v[140:143], v[206:209], v[72:75]
	s_barrier
	s_add_i32 s47, s39, s27
	v_lshl_add_u64 v[170:171], s[18:19], 0, v[150:151]
	s_mov_b32 m0, s47
	ds_read_b128 v[210:213], v180
	ds_read_b128 v[214:217], v180 offset:1024
	ds_read_b128 v[218:221], v180 offset:2048
	ds_read_b128 v[222:225], v180 offset:3072
	global_load_lds_dwordx4 v[170:171], off
	s_add_i32 m0, s47, 0x2000
	v_lshl_add_u64 v[226:227], s[18:19], 0, v[154:155]
	global_load_lds_dwordx4 v[226:227], off
	s_barrier
	s_waitcnt lgkmcnt(0)
	v_mfma_f32_16x16x32_bf16 v[116:119], v[210:213], v[144:147], v[116:119]
	v_mfma_f32_16x16x32_bf16 v[112:115], v[218:221], v[144:147], v[112:115]
	v_mfma_f32_16x16x32_bf16 v[100:103], v[210:213], v[186:189], v[100:103]
	v_mfma_f32_16x16x32_bf16 v[96:99], v[218:221], v[186:189], v[96:99]
	v_mfma_f32_16x16x32_bf16 v[84:87], v[210:213], v[194:197], v[84:87]
	v_mfma_f32_16x16x32_bf16 v[80:83], v[218:221], v[194:197], v[80:83]
	v_mfma_f32_16x16x32_bf16 v[68:71], v[210:213], v[202:205], v[68:71]
	v_mfma_f32_16x16x32_bf16 v[64:67], v[218:221], v[202:205], v[64:67]
	v_mfma_f32_16x16x32_bf16 v[116:119], v[214:217], v[182:185], v[116:119]
	v_mfma_f32_16x16x32_bf16 v[112:115], v[222:225], v[182:185], v[112:115]
	v_mfma_f32_16x16x32_bf16 v[100:103], v[214:217], v[190:193], v[100:103]
	v_mfma_f32_16x16x32_bf16 v[96:99], v[222:225], v[190:193], v[96:99]
	v_mfma_f32_16x16x32_bf16 v[84:87], v[214:217], v[198:201], v[84:87]
	v_mfma_f32_16x16x32_bf16 v[80:83], v[222:225], v[198:201], v[80:83]
	v_mfma_f32_16x16x32_bf16 v[68:71], v[214:217], v[206:209], v[68:71]
	v_mfma_f32_16x16x32_bf16 v[64:67], v[222:225], v[206:209], v[64:67]
	s_mov_b32 m0, s28
	v_lshl_add_u64 v[228:229], s[20:21], 0, v[148:149]
	s_barrier
	ds_read_b128 v[144:147], v177 offset:16384
	ds_read_b128 v[182:185], v177 offset:17408
	ds_read_b128 v[186:189], v177 offset:18432
	ds_read_b128 v[190:193], v177 offset:19456
	ds_read_b128 v[194:197], v177 offset:20480
	ds_read_b128 v[198:201], v177 offset:21504
	ds_read_b128 v[202:205], v177 offset:22528
	ds_read_b128 v[206:209], v177 offset:23552
	global_load_lds_dwordx4 v[228:229], off
	s_mov_b32 m0, s29
	v_lshl_add_u64 v[230:231], s[20:21], 0, v[152:153]
	global_load_lds_dwordx4 v[230:231], off
	s_barrier
	s_waitcnt lgkmcnt(0)
	v_mfma_f32_16x16x32_bf16 v[60:63], v[128:131], v[144:147], v[60:63]
	v_mfma_f32_16x16x32_bf16 v[56:59], v[136:139], v[144:147], v[56:59]
	v_mfma_f32_16x16x32_bf16 v[44:47], v[128:131], v[186:189], v[44:47]
	v_mfma_f32_16x16x32_bf16 v[40:43], v[136:139], v[186:189], v[40:43]
	v_mfma_f32_16x16x32_bf16 v[28:31], v[128:131], v[194:197], v[28:31]
	v_mfma_f32_16x16x32_bf16 v[24:27], v[136:139], v[194:197], v[24:27]
	v_mfma_f32_16x16x32_bf16 v[12:15], v[128:131], v[202:205], v[12:15]
	v_mfma_f32_16x16x32_bf16 v[8:11], v[136:139], v[202:205], v[8:11]
	v_mfma_f32_16x16x32_bf16 v[60:63], v[132:135], v[182:185], v[60:63]
	v_mfma_f32_16x16x32_bf16 v[56:59], v[140:143], v[182:185], v[56:59]
	v_mfma_f32_16x16x32_bf16 v[44:47], v[132:135], v[190:193], v[44:47]
	v_mfma_f32_16x16x32_bf16 v[40:43], v[140:143], v[190:193], v[40:43]
	v_mfma_f32_16x16x32_bf16 v[28:31], v[132:135], v[198:201], v[28:31]
	v_mfma_f32_16x16x32_bf16 v[24:27], v[140:143], v[198:201], v[24:27]
	v_mfma_f32_16x16x32_bf16 v[12:15], v[132:135], v[206:209], v[12:15]
	v_mfma_f32_16x16x32_bf16 v[8:11], v[140:143], v[206:209], v[8:11]
	s_barrier
	s_add_u32 s48, s18, 0x40000
	s_addc_u32 s49, s19, 0
	s_add_i32 s47, s40, s27
	s_mov_b32 m0, s47
	v_lshl_add_u64 v[128:129], s[48:49], 0, v[150:151]
	global_load_lds_dwordx4 v[128:129], off
	s_add_i32 m0, s47, 0x2000
	v_lshl_add_u64 v[128:129], s[48:49], 0, v[154:155]
	global_load_lds_dwordx4 v[128:129], off
	s_waitcnt vmcnt(6)
	s_barrier
; #define PG8_STAGE(bufoff, gbase, voff) do { _Pragma("unroll") for (int _i = 0; _i < 2; ++_i) \
;         __builtin_amdgcn_global_load_lds((const unsigned*)((const char*)(gbase) + (voff)[_i]), (LAS unsigned*)(lds + (bufoff) + ldsw + _i * 8192), 16, 0, 0); } while (0)
; #define PG8_LDA(dst, b, h) do { _Pragma("unroll") for (int m = 0; m < 4; ++m) _Pragma("unroll") for (int k = 0; k < 2; ++k) dst[m][k] = *(const LAS bf16x8*)(lds + PG8_SA(b, h) + aoff + m * 2048 + k * 1024); } while (0)
; #define PG8_LDB(dst, b, h) do { _Pragma("unroll") for (int n = 0; n < 2; ++n) _Pragma("unroll") for (int k = 0; k < 2; ++k) dst[n][k] = *(const LAS bf16x8*)(lds + PG8_SB(b, h) + boff + n * 2048 + k * 1024); } while (0)
; #define PG8_MMA(ai, bj, At, Bt) do { __builtin_amdgcn_s_setprio(1); _Pragma("unroll") for (int m = 0; m < 4; ++m) _Pragma("unroll") for (int n = 0; n < 2; ++n) _Pragma("unroll") for (int k = 0; k < 2; ++k) \
;         acc[ai][bj][m][n] = __builtin_amdgcn_mfma_f32_16x16x32_bf16(Bt[n][k], At[m][k], acc[ai][bj][m][n], 0, 0, 0); __builtin_amdgcn_s_setprio(0); } while (0)
; #define PG8_WAIT_V(n) asm volatile("s_waitcnt vmcnt(" #n ")" ::: "memory")
; #define PG8_WAIT_L(n) asm volatile("s_waitcnt lgkmcnt(" #n ")" ::: "memory")
; #define PG8_BAR __builtin_amdgcn_s_barrier()
; #define PG8_SCHED __builtin_amdgcn_sched_barrier(0)
; template <class Epi, class Sched>
; __device__ __forceinline__ void gemm_phase(const int wv, LAS unsigned char* lds, const Gemm g, const Sched& S, const Epi& E) {
;     ...
;             PG8_WAIT_V(6); PG8_BAR; PG8_MMA(1, 1, At, B1); PG8_BAR;
;             PG8_LDB(B0, 1, 0); PG8_SCHED; PG8_LDA(At, 1, 0); PG8_STAGE(PG8_SA(0, 1), a2 + hstepA, voffA);
;             PG8_WAIT_L(8); PG8_BAR; PG8_WAIT_L(0); PG8_MMA(0, 0, At, B0); PG8_BAR; PG8_SCHED;
;             PG8_LDB(B1, 1, 1); PG8_STAGE(PG8_SB(1, 0), b3, voffB);
;             PG8_BAR; PG8_WAIT_L(0); PG8_MMA(0, 1, At, B1); PG8_BAR;
;             PG8_LDA(At, 1, 1); PG8_STAGE(PG8_SA(1, 0), a3, voffA);
;             PG8_BAR; PG8_WAIT_L(0); PG8_MMA(1, 0, At, B0); PG8_BAR; PG8_SCHED;
;             PG8_STAGE(PG8_SB(1, 1), b3 + hstepB, voffB);
;             PG8_WAIT_V(6); PG8_BAR; PG8_MMA(1, 1, At, B1); PG8_BAR;
	v_mfma_f32_16x16x32_bf16 v[52:55], v[210:213], v[144:147], v[52:55]
	v_mfma_f32_16x16x32_bf16 v[48:51], v[218:221], v[144:147], v[48:51]
	v_mfma_f32_16x16x32_bf16 v[36:39], v[210:213], v[186:189], v[36:39]
	v_mfma_f32_16x16x32_bf16 v[32:35], v[218:221], v[186:189], v[32:35]
	v_mfma_f32_16x16x32_bf16 v[20:23], v[210:213], v[194:197], v[20:23]
	v_mfma_f32_16x16x32_bf16 v[16:19], v[218:221], v[194:197], v[16:19]
	v_mfma_f32_16x16x32_bf16 v[4:7], v[210:213], v[202:205], v[4:7]
	v_mfma_f32_16x16x32_bf16 v[0:3], v[218:221], v[202:205], v[0:3]
	v_mfma_f32_16x16x32_bf16 v[52:55], v[214:217], v[182:185], v[52:55]
	v_mfma_f32_16x16x32_bf16 v[48:51], v[222:225], v[182:185], v[48:51]
	v_mfma_f32_16x16x32_bf16 v[36:39], v[214:217], v[190:193], v[36:39]
	v_mfma_f32_16x16x32_bf16 v[32:35], v[222:225], v[190:193], v[32:35]
	v_mfma_f32_16x16x32_bf16 v[20:23], v[214:217], v[198:201], v[20:23]
	v_mfma_f32_16x16x32_bf16 v[16:19], v[222:225], v[198:201], v[16:19]
	v_mfma_f32_16x16x32_bf16 v[4:7], v[214:217], v[206:209], v[4:7]
	v_mfma_f32_16x16x32_bf16 v[0:3], v[222:225], v[206:209], v[0:3]
	s_add_i32 s47, 0, 0x18000
	v_add_u32_e32 v140, s47, v173
	s_barrier
	ds_read_b128 v[128:131], v140
	ds_read_b128 v[132:135], v140 offset:1024
	ds_read_b128 v[136:139], v140 offset:2048
	ds_read_b128 v[140:143], v140 offset:3072
	s_add_u32 s20, s20, 0x40000
	s_addc_u32 s21, s21, 0
	s_mov_b32 m0, s30
	v_lshl_add_u64 v[210:211], s[20:21], 0, v[148:149]
	ds_read_b128 v[144:147], v177 offset:32768
	ds_read_b128 v[182:185], v177 offset:33792
	ds_read_b128 v[186:189], v177 offset:34816
	ds_read_b128 v[190:193], v177 offset:35840
	ds_read_b128 v[194:197], v177 offset:36864
	ds_read_b128 v[198:201], v177 offset:37888
	ds_read_b128 v[202:205], v177 offset:38912
	ds_read_b128 v[206:209], v177 offset:39936
	global_load_lds_dwordx4 v[210:211], off
	s_mov_b32 m0, s31
	v_lshl_add_u64 v[210:211], s[20:21], 0, v[152:153]
	global_load_lds_dwordx4 v[210:211], off
	s_waitcnt lgkmcnt(8)
	s_barrier
	s_waitcnt lgkmcnt(0)
	v_mfma_f32_16x16x32_bf16 v[124:127], v[128:131], v[144:147], v[124:127]
	v_mfma_f32_16x16x32_bf16 v[120:123], v[136:139], v[144:147], v[120:123]
	v_mfma_f32_16x16x32_bf16 v[108:111], v[128:131], v[186:189], v[108:111]
	v_mfma_f32_16x16x32_bf16 v[104:107], v[136:139], v[186:189], v[104:107]
	v_mfma_f32_16x16x32_bf16 v[92:95], v[128:131], v[194:197], v[92:95]
	v_mfma_f32_16x16x32_bf16 v[88:91], v[136:139], v[194:197], v[88:91]
	v_mfma_f32_16x16x32_bf16 v[76:79], v[128:131], v[202:205], v[76:79]
	v_mfma_f32_16x16x32_bf16 v[72:75], v[136:139], v[202:205], v[72:75]
	v_mfma_f32_16x16x32_bf16 v[124:127], v[132:135], v[182:185], v[124:127]
	v_mfma_f32_16x16x32_bf16 v[120:123], v[140:143], v[182:185], v[120:123]
	v_mfma_f32_16x16x32_bf16 v[108:111], v[132:135], v[190:193], v[108:111]
	v_mfma_f32_16x16x32_bf16 v[104:107], v[140:143], v[190:193], v[104:107]
	v_mfma_f32_16x16x32_bf16 v[92:95], v[132:135], v[198:201], v[92:95]
	v_mfma_f32_16x16x32_bf16 v[88:91], v[140:143], v[198:201], v[88:91]
	v_mfma_f32_16x16x32_bf16 v[76:79], v[132:135], v[206:209], v[76:79]
	v_mfma_f32_16x16x32_bf16 v[72:75], v[140:143], v[206:209], v[72:75]
	s_barrier
	s_add_i32 s20, 0, 0x1c000
	s_add_i32 s21, s47, s27
	v_add_u32_e32 v156, s20, v173
	v_lshl_add_u64 v[170:171], v[170:171], 0, s[4:5]
	s_mov_b32 m0, s21
	ds_read_b128 v[210:213], v156
	ds_read_b128 v[214:217], v156 offset:1024
	ds_read_b128 v[218:221], v156 offset:2048
	ds_read_b128 v[222:225], v156 offset:3072
	global_load_lds_dwordx4 v[170:171], off
	s_add_i32 m0, s21, 0x2000
	v_lshl_add_u64 v[170:171], v[226:227], 0, s[4:5]
	global_load_lds_dwordx4 v[170:171], off
	s_barrier
	s_waitcnt lgkmcnt(0)
	v_mfma_f32_16x16x32_bf16 v[116:119], v[210:213], v[144:147], v[116:119]
	v_mfma_f32_16x16x32_bf16 v[112:115], v[218:221], v[144:147], v[112:115]
	v_mfma_f32_16x16x32_bf16 v[100:103], v[210:213], v[186:189], v[100:103]
	v_mfma_f32_16x16x32_bf16 v[96:99], v[218:221], v[186:189], v[96:99]
	v_mfma_f32_16x16x32_bf16 v[84:87], v[210:213], v[194:197], v[84:87]
	v_mfma_f32_16x16x32_bf16 v[80:83], v[218:221], v[194:197], v[80:83]
	v_mfma_f32_16x16x32_bf16 v[68:71], v[210:213], v[202:205], v[68:71]
	v_mfma_f32_16x16x32_bf16 v[64:67], v[218:221], v[202:205], v[64:67]
	v_mfma_f32_16x16x32_bf16 v[116:119], v[214:217], v[182:185], v[116:119]
	v_mfma_f32_16x16x32_bf16 v[112:115], v[222:225], v[182:185], v[112:115]
	v_mfma_f32_16x16x32_bf16 v[100:103], v[214:217], v[190:193], v[100:103]
	v_mfma_f32_16x16x32_bf16 v[96:99], v[222:225], v[190:193], v[96:99]
	v_mfma_f32_16x16x32_bf16 v[84:87], v[214:217], v[198:201], v[84:87]
	v_mfma_f32_16x16x32_bf16 v[80:83], v[222:225], v[198:201], v[80:83]
	v_mfma_f32_16x16x32_bf16 v[68:71], v[214:217], v[206:209], v[68:71]
	v_mfma_f32_16x16x32_bf16 v[64:67], v[222:225], v[206:209], v[64:67]
	s_mov_b32 m0, s37
	v_lshl_add_u64 v[170:171], v[228:229], 0, s[4:5]
	s_barrier
	ds_read_b128 v[144:147], v177 offset:49152
	ds_read_b128 v[182:185], v177 offset:50176
	ds_read_b128 v[186:189], v177 offset:51200
	ds_read_b128 v[190:193], v177 offset:52224
	ds_read_b128 v[194:197], v177 offset:53248
	ds_read_b128 v[198:201], v177 offset:54272
	ds_read_b128 v[202:205], v177 offset:55296
	ds_read_b128 v[206:209], v177 offset:56320
	global_load_lds_dwordx4 v[170:171], off
	s_mov_b32 m0, s38
	v_lshl_add_u64 v[170:171], v[230:231], 0, s[4:5]
	global_load_lds_dwordx4 v[170:171], off
	s_barrier
; #define PG8_STAGE(bufoff, gbase, voff) do { _Pragma("unroll") for (int _i = 0; _i < 2; ++_i) \
;         __builtin_amdgcn_global_load_lds((const unsigned*)((const char*)(gbase) + (voff)[_i]), (LAS unsigned*)(lds + (bufoff) + ldsw + _i * 8192), 16, 0, 0); } while (0)
; #define PG8_MMA(ai, bj, At, Bt) do { __builtin_amdgcn_s_setprio(1); _Pragma("unroll") for (int m = 0; m < 4; ++m) _Pragma("unroll") for (int n = 0; n < 2; ++n) _Pragma("unroll") for (int k = 0; k < 2; ++k) \
;         acc[ai][bj][m][n] = __builtin_amdgcn_mfma_f32_16x16x32_bf16(Bt[n][k], At[m][k], acc[ai][bj][m][n], 0, 0, 0); __builtin_amdgcn_s_setprio(0); } while (0)
; #define PG8_WAIT_V(n) asm volatile("s_waitcnt vmcnt(" #n ")" ::: "memory")
; #define PG8_WAIT_L(n) asm volatile("s_waitcnt lgkmcnt(" #n ")" ::: "memory")
; #define PG8_BAR __builtin_amdgcn_s_barrier()
; #define PG8_SCHED __builtin_amdgcn_sched_barrier(0)
; template <class Epi, class Sched>
; __device__ __forceinline__ void gemm_phase(const int wv, LAS unsigned char* lds, const Gemm g, const Sched& S, const Epi& E) {
;     ...
;             PG8_BAR; PG8_WAIT_L(0); PG8_MMA(1, 0, At, B0); PG8_BAR; PG8_SCHED;
;             PG8_STAGE(PG8_SB(1, 1), b3 + hstepB, voffB);
;             PG8_WAIT_V(6); PG8_BAR; PG8_MMA(1, 1, At, B1); PG8_BAR;
;     __device__ __forceinline__ void operator()(const f32x4 (&acc)[2][2][4][2], const Unit& u, int wr, int wc, int fr, int fq) const {
;         const int row0 = u.pm * 256 + wr * 64 + fr; const int col0 = u.pn * 256 + wc * 32 + 8 * fq;
;         f32x4 sq[2][4];
; #pragma unroll
;         for (int ai = 0; ai < 2; ++ai)
; #pragma unroll
;             for (int m = 0; m < 4; ++m) sq[ai][m] = *(const f32x4*)(ss2 + (size_t)(row0 + ai * 128 + m * 16) * 16 + 4 * fq);
	s_waitcnt lgkmcnt(0)
	v_mfma_f32_16x16x32_bf16 v[60:63], v[128:131], v[144:147], v[60:63]
	v_mfma_f32_16x16x32_bf16 v[56:59], v[136:139], v[144:147], v[56:59]
	v_mfma_f32_16x16x32_bf16 v[44:47], v[128:131], v[186:189], v[44:47]
	v_mfma_f32_16x16x32_bf16 v[40:43], v[136:139], v[186:189], v[40:43]
	v_mfma_f32_16x16x32_bf16 v[28:31], v[128:131], v[194:197], v[28:31]
	v_mfma_f32_16x16x32_bf16 v[24:27], v[136:139], v[194:197], v[24:27]
	v_mfma_f32_16x16x32_bf16 v[12:15], v[128:131], v[202:205], v[12:15]
	v_mfma_f32_16x16x32_bf16 v[8:11], v[136:139], v[202:205], v[8:11]
	v_mfma_f32_16x16x32_bf16 v[60:63], v[132:135], v[182:185], v[60:63]
	v_mfma_f32_16x16x32_bf16 v[56:59], v[140:143], v[182:185], v[56:59]
	v_mfma_f32_16x16x32_bf16 v[44:47], v[132:135], v[190:193], v[44:47]
	v_mfma_f32_16x16x32_bf16 v[40:43], v[140:143], v[190:193], v[40:43]
	v_mfma_f32_16x16x32_bf16 v[28:31], v[132:135], v[198:201], v[28:31]
	v_mfma_f32_16x16x32_bf16 v[24:27], v[140:143], v[198:201], v[24:27]
	v_mfma_f32_16x16x32_bf16 v[12:15], v[132:135], v[206:209], v[12:15]
	v_mfma_f32_16x16x32_bf16 v[8:11], v[140:143], v[206:209], v[8:11]
	s_barrier
	s_add_u32 s18, s18, 0x40080
	s_addc_u32 s19, s19, 0
	s_add_i32 s20, s20, s27
	s_mov_b32 m0, s20
	v_lshl_add_u64 v[128:129], s[18:19], 0, v[150:151]
	global_load_lds_dwordx4 v[128:129], off
	s_add_i32 m0, s20, 0x2000
	v_lshl_add_u64 v[128:129], s[18:19], 0, v[154:155]
	global_load_lds_dwordx4 v[128:129], off
	s_waitcnt vmcnt(6)
	s_barrier
	v_mfma_f32_16x16x32_bf16 v[52:55], v[210:213], v[144:147], v[52:55]
	v_mfma_f32_16x16x32_bf16 v[48:51], v[218:221], v[144:147], v[48:51]
	v_mfma_f32_16x16x32_bf16 v[36:39], v[210:213], v[186:189], v[36:39]
	v_mfma_f32_16x16x32_bf16 v[32:35], v[218:221], v[186:189], v[32:35]
	v_mfma_f32_16x16x32_bf16 v[20:23], v[210:213], v[194:197], v[20:23]
	v_mfma_f32_16x16x32_bf16 v[16:19], v[218:221], v[194:197], v[16:19]
	v_mfma_f32_16x16x32_bf16 v[4:7], v[210:213], v[202:205], v[4:7]
	v_mfma_f32_16x16x32_bf16 v[0:3], v[218:221], v[202:205], v[0:3]
	v_mfma_f32_16x16x32_bf16 v[52:55], v[214:217], v[182:185], v[52:55]
	v_mfma_f32_16x16x32_bf16 v[48:51], v[222:225], v[182:185], v[48:51]
	v_mfma_f32_16x16x32_bf16 v[36:39], v[214:217], v[190:193], v[36:39]
	v_mfma_f32_16x16x32_bf16 v[32:35], v[222:225], v[190:193], v[32:35]
	v_mfma_f32_16x16x32_bf16 v[20:23], v[214:217], v[198:201], v[20:23]
	v_mfma_f32_16x16x32_bf16 v[16:19], v[222:225], v[198:201], v[16:19]
	v_mfma_f32_16x16x32_bf16 v[4:7], v[214:217], v[206:209], v[4:7]
	v_mfma_f32_16x16x32_bf16 v[0:3], v[222:225], v[206:209], v[0:3]
	s_add_i32 s46, s46, 2
	s_add_u32 s16, s16, 0x100
	s_addc_u32 s17, s17, 0
	s_add_u32 s44, s44, 0x100
	s_addc_u32 s45, s45, 0
	s_cmp_gt_u32 s46, 13
	s_barrier
	s_cbranch_scc0 .LBB0_725
	s_lshl_b32 s7, s14, 8
	s_add_i32 s7, s7, s35
	v_or_b32_e32 v132, s7, v172
	v_ashrrev_i32_e32 v133, 31, v132
	v_lshlrev_b64 v[128:129], 6, v[132:133]
	v_lshl_add_u64 v[134:135], v[158:159], 0, v[128:129]
	v_or_b32_e32 v136, 16, v132
	v_ashrrev_i32_e32 v137, 31, v136
	v_lshlrev_b64 v[136:137], 6, v[136:137]
	v_lshl_add_u64 v[136:137], v[158:159], 0, v[136:137]
	v_or_b32_e32 v136, 32, v132
	v_or_b32_e32 v138, 48, v132
	v_add_u32_e32 v170, 0x80, v132
	v_lshlrev_b32_e32 v132, 7, v132
	v_ashrrev_i32_e32 v137, 31, v136
	v_ashrrev_i32_e32 v139, 31, v138
	v_and_b32_e32 v156, 0x6780, v132
	v_lshlrev_b64 v[132:133], 6, v[136:137]
	v_lshlrev_b64 v[136:137], 6, v[138:139]
	v_lshl_add_u64 v[132:133], v[158:159], 0, v[132:133]
	v_lshl_add_u64 v[136:137], v[158:159], 0, v[136:137]
	v_ashrrev_i32_e32 v171, 31, v170
	v_lshlrev_b64 v[138:139], 6, v[170:171]
	v_add_co_u32_e32 v190, vcc, s33, v134
	s_lshl_b32 s9, s15, 8
	s_nop 0
	v_addc_co_u32_e32 v191, vcc, 0, v135, vcc
	s_or_b32 s9, s9, s36
	s_ashr_i32 s14, s7, 2
	s_ashr_i32 s7, s9, 6
	s_and_b32 s16, s14, 0xffffffc0
	s_add_i32 s14, s16, s7
	s_ashr_i32 s15, s14, 31
	s_lshl_b64 s[14:15], s[14:15], 15
	s_add_u32 s14, s2, s14
	v_lshl_add_u64 v[138:139], v[158:159], 0, v[138:139]
	s_addc_u32 s15, s3, s15
	v_mov_b32_e32 v169, v157
	s_or_b32 s9, s7, 2
	s_add_i32 s16, s16, s9
	s_ashr_i32 s17, s16, 31
	s_lshl_b64 s[16:17], s[16:17], 15
	s_add_u32 s16, s2, s16
	s_addc_u32 s17, s3, s17
	s_mov_b64 s[18:19], s[12:13]
	v_mov_b32_e32 v128, v232
	v_mov_b32_e32 v129, v233
	v_mov_b32_e32 v130, v234
	v_mov_b32_e32 v131, v235
	v_mov_b32_e32 v182, v236
	v_mov_b32_e32 v183, v237
	v_mov_b32_e32 v184, v238
	v_mov_b32_e32 v185, v239
	v_mov_b32_e32 v186, v240
	v_mov_b32_e32 v187, v241
	v_mov_b32_e32 v188, v242
	v_mov_b32_e32 v189, v243
	v_mov_b32_e32 v144, v244
	v_mov_b32_e32 v145, v245
	v_mov_b32_e32 v146, v246
	v_mov_b32_e32 v147, v247
	s_cmp_lg_u64 s[0:1], 0
	s_cbranch_scc1 .Lup_nopf
	s_lshl_b32 s70, s8, 8
	s_add_i32 s70, s70, s35
	v_or_b32_e32 v248, s70, v172
	v_ashrrev_i32_e32 v249, 31, v248
	v_lshlrev_b64 v[248:249], 6, v[248:249]
	v_lshl_add_u64 v[248:249], v[158:159], 0, v[248:249]
	global_load_dwordx4 v[232:235], v[248:249], off
	global_load_dwordx4 v[236:239], v[248:249], off offset:1024
	global_load_dwordx4 v[240:243], v[248:249], off offset:2048
	global_load_dwordx4 v[244:247], v[248:249], off offset:3072
